# sb item prologue: q wait moved below K/V load issue (counted wait), second q load issued early
# baseline (speedup 1.0000x reference)
; #define LAS __attribute__((address_space(3)))
; __device__ __forceinline__ float bflo(unsigned u) { return __uint_as_float(u << 16); }
; __device__ __forceinline__ float bfhi(unsigned u) { return __uint_as_float(u & 0xffff0000u); }
; __device__ __forceinline__ float sx(float v, int m, int lane) { return __builtin_bit_cast(float, __builtin_amdgcn_ds_bpermute((lane ^ m) << 2, __builtin_bit_cast(int, v))); }
; __device__ __forceinline__ void sb_item(const bf16_t* hbuf, const float* kmax2, bf16_t* mixed, LAS bf16_t* vT, int item, int lane) {
;     const int bh = item >> 10, qt = item & 1023, b = bh / 6, h = bh % 6, tq0 = qt * 16; const size_t row0 = (size_t)b * SEQ + tq0;
;     const int r = lane & 15, q = lane >> 4;
;     bf16x8 qf[2]; float bound, carry = 0.f;
;     const float km2 = kmax2[bh];
;     { float s = 0.f;
; #pragma unroll
;       for (int ks = 0; ks < 2; ++ks) { const u32x4 v = *(const u32x4*)(hbuf + (row0 + r) * INWP + C_SBQ + h * 64 + 32 * ks + 8 * q); qf[ks] = as_bf16x8(v);
;           s += bflo(v.x) * bflo(v.x) + bfhi(v.x) * bfhi(v.x) + bflo(v.y) * bflo(v.y) + bfhi(v.y) * bfhi(v.y) + bflo(v.z) * bflo(v.z) + bfhi(v.z) * bfhi(v.z) + bflo(v.w) * bflo(v.w) + bfhi(v.w) * bfhi(v.w); }
;       s += sx(s, 16, lane); s += sx(s, 32, lane);
;       bound = sqrtf(s * km2) * 0.125f * 1.01f + 0.05f; }
;     const int qpos = tq0 + r;
;     f32x4 O[4];
; #pragma unroll
;     for (int et = 0; et < 4; ++et) O[et] = (f32x4){0.f, 0.f, 0.f, 0.f};
;     const int cr = lane >> 3, dc = lane & 7;
;     const bf16_t* seqp = hbuf + (size_t)b * SEQ * INWP + h * 64;
;     u32x4 vreg[8], kreg[8];
;     { const int k0 = tq0 + 16 - 64;
; #pragma unroll
;       for (int i = 0; i < 8; ++i) vreg[i] = *(const u32x4*)(seqp + (size_t)max(k0 + cr + 8 * i, 0) * INWP + C_SBV + 8 * dc);
; #pragma unroll
;       for (int i = 0; i < 8; ++i) kreg[i] = *(const u32x4*)(seqp + (size_t)max(k0 + 16 * (i >> 1) + r, 0) * INWP + C_SBK + 32 * (i & 1) + 8 * q); }
.LBB0_234:
	s_and_b32 s98, s12, 3
	s_lshl_b32 s98, s98, 3
	s_bfe_u32 s99, s12, 0x30002
	s_add_i32 s98, s98, s99
	s_and_b32 s99, s12, 0xffffffe0
	s_or_b32 s98, s98, s99
	s_ashr_i32 s0, s98, 10
	s_mul_hi_i32 s1, s0, 0x2aaaaaab
	s_lshr_b32 s17, s1, 31
	s_add_i32 s20, s1, s17
	s_mul_i32 s1, s20, 6
	s_sub_i32 s17, s0, s1
	s_lshl_b32 s1, s98, 4
	s_ashr_i32 s21, s20, 31
	s_and_b32 s26, s1, 0x3ff0
	s_lshl_b64 s[22:23], s[20:21], 14
	s_ashr_i32 s1, s0, 31
	s_or_b32 s21, s22, s26
	s_lshl_b64 s[0:1], s[0:1], 2
	s_add_u32 s0, s75, s0
	s_addc_u32 s1, s74, s1
	v_or_b32_e32 v34, s21, v122
	v_mov_b64_e32 v[8:9], s[42:43]
	s_lshl_b32 s72, s17, 6
	global_load_dword v16, v33, s[0:1] offset:1024
	v_mad_u64_u32 v[8:9], s[0:1], v34, s5, v[8:9]
	s_ashr_i32 s73, s72, 31
	v_mov_b32_e32 v35, s23
	v_mad_i32_i24 v9, s23, v207, v9
	s_lshl_b64 s[22:23], s[72:73], 1
	v_lshl_add_u64 v[8:9], v[8:9], 0, s[22:23]
	v_lshlrev_b32_e32 v32, 1, v124
	v_lshl_add_u64 v[12:13], v[8:9], 0, v[32:33]
	global_load_dwordx4 v[8:11], v[12:13], off offset:512
	global_load_dwordx4 v[212:215], v[12:13], off offset:576
	s_mov_b32 s0, 0xf800000
	v_lshlrev_b32_e32 v88, 1, v126
	v_mov_b32_e32 v89, v33
	v_mov_b32_e32 v153, 0
	v_or_b32_e32 v155, s26, v122
	v_mov_b32_e32 v100, 0
	v_mov_b32_e32 v101, v153
	v_mov_b32_e32 v102, v153
	v_mov_b32_e32 v103, v153
	v_mov_b32_e32 v96, 0
	v_mov_b32_e32 v97, v153
	v_mov_b32_e32 v98, v153
	v_mov_b32_e32 v99, v153
	v_mov_b32_e32 v92, 0
	v_mov_b32_e32 v93, v153
	v_mov_b32_e32 v94, v153
	v_mov_b32_e32 v95, v153
	v_mov_b32_e32 v90, v153
	v_mov_b32_e32 v91, v153
	s_waitcnt vmcnt(0)
	v_and_b32_e32 v15, 0xffff0000, v8
	v_lshlrev_b32_e32 v14, 16, v8
	v_mul_f32_e32 v17, v15, v15
	v_fmac_f32_e32 v17, v14, v14
	v_lshlrev_b32_e32 v14, 16, v9
	v_fmac_f32_e32 v17, v14, v14
	v_and_b32_e32 v14, 0xffff0000, v9
	v_fmac_f32_e32 v17, v14, v14
	v_lshlrev_b32_e32 v14, 16, v10
	v_fmac_f32_e32 v17, v14, v14
	v_and_b32_e32 v14, 0xffff0000, v10
	v_fmac_f32_e32 v17, v14, v14
	v_lshlrev_b32_e32 v14, 16, v11
	v_fmac_f32_e32 v17, v14, v14
	v_and_b32_e32 v14, 0xffff0000, v11
	v_fmac_f32_e32 v17, v14, v14
	v_mov_b32_e32 v12, v212
	v_mov_b32_e32 v13, v213
	v_mov_b32_e32 v14, v214
	v_mov_b32_e32 v15, v215
	v_and_b32_e32 v19, 0xffff0000, v12
	v_lshlrev_b32_e32 v18, 16, v12
	v_mul_f32_e32 v19, v19, v19
	v_fmac_f32_e32 v19, v18, v18
	v_lshlrev_b32_e32 v18, 16, v13
	v_fmac_f32_e32 v19, v18, v18
	v_and_b32_e32 v18, 0xffff0000, v13
	v_fmac_f32_e32 v19, v18, v18
	v_lshlrev_b32_e32 v18, 16, v14
	v_fmac_f32_e32 v19, v18, v18
	v_and_b32_e32 v18, 0xffff0000, v14
	v_fmac_f32_e32 v19, v18, v18
	v_lshlrev_b32_e32 v18, 16, v15
	v_fmac_f32_e32 v19, v18, v18
	v_and_b32_e32 v18, 0xffff0000, v15
	v_fmac_f32_e32 v19, v18, v18
	v_add_f32_e32 v17, v17, v19
	ds_bpermute_b32 v18, v132, v17
	s_waitcnt lgkmcnt(0)
	v_add_f32_e32 v17, v17, v18
	ds_bpermute_b32 v18, v133, v17
	s_waitcnt lgkmcnt(0)
	v_add_f32_e32 v17, v17, v18
	v_mul_f32_e32 v16, v16, v17
	v_cmp_gt_f32_e32 vcc, s0, v16
	v_mul_f32_e32 v17, 0x4f800000, v16
	s_nop 0
	v_cndmask_b32_e32 v16, v16, v17, vcc
	v_sqrt_f32_e32 v17, v16
	s_nop 0
	v_add_u32_e32 v18, -1, v17
	v_fma_f32 v19, -v18, v17, v16
	v_cmp_ge_f32_e64 s[0:1], 0, v19
	v_add_u32_e32 v19, 1, v17
	s_nop 0
	v_cndmask_b32_e64 v18, v17, v18, s[0:1]
	v_fma_f32 v17, -v19, v17, v16
	v_cmp_lt_f32_e64 s[0:1], 0, v17
	s_nop 1
	v_cndmask_b32_e64 v17, v18, v19, s[0:1]
	s_mul_i32 s1, s20, 0x6000000
	s_mul_hi_i32 s0, s20, 0x6000000
	s_add_u32 s1, s42, s1
	v_mul_f32_e32 v18, 0x37800000, v17
	s_addc_u32 s17, s43, s0
	v_cndmask_b32_e32 v17, v17, v18, vcc
	v_cmp_class_f32_e32 vcc, v16, v209
	s_add_u32 s0, s1, s22
	s_addc_u32 s1, s17, s23
	v_cndmask_b32_e32 v16, v17, v16, vcc
	s_sub_i32 s17, s26, 48
	v_mul_f32_e32 v16, 0x3e000000, v16
	v_or_b32_e32 v48, s17, v122
	v_or_b32_e32 v86, s17, v134
	v_fmamk_f32 v154, v16, 0x3f8147ae, v170
	v_max_i32_e32 v16, 0xffffffd0, v48
	v_max_i32_e32 v24, 0xffffffe0, v48
	v_max_i32_e32 v40, -16, v48
	v_max_i32_e32 v64, 0xffffffd8, v86
	v_max_i32_e32 v68, 0xffffffe0, v86
	v_add_u32_e32 v16, 48, v16
	v_mov_b64_e32 v[84:85], s[0:1]
	v_add_u32_e32 v24, 32, v24
	v_add_u32_e32 v40, 16, v40
	v_max_i32_e32 v48, 0, v48
	v_add_u32_e32 v64, 40, v64
	v_add_u32_e32 v68, 32, v68
	v_mad_u64_u32 v[16:17], s[20:21], v16, s5, v[84:85]
	v_mad_u64_u32 v[24:25], s[20:21], v24, s5, v[84:85]
	v_mad_u64_u32 v[40:41], s[20:21], v40, s5, v[84:85]
	v_mad_u64_u32 v[48:49], s[20:21], v48, s5, v[84:85]
	v_mad_u64_u32 v[64:65], s[20:21], v64, s5, v[84:85]
	v_mad_u64_u32 v[68:69], s[20:21], v68, s5, v[84:85]
	v_lshl_add_u64 v[20:21], v[16:17], 0, v[32:33]
	v_lshl_add_u64 v[28:29], v[24:25], 0, v[32:33]
	v_lshl_add_u64 v[44:45], v[40:41], 0, v[32:33]
	v_lshl_add_u64 v[52:53], v[48:49], 0, v[32:33]
	v_lshl_add_u64 v[64:65], v[64:65], 0, v[88:89]
	v_lshl_add_u64 v[68:69], v[68:69], 0, v[88:89]
	global_load_dwordx4 v[16:19], v[20:21], off offset:1344
	s_nop 0
	global_load_dwordx4 v[20:23], v[20:21], off offset:1280
	s_nop 0
	global_load_dwordx4 v[24:27], v[28:29], off offset:1344
	s_nop 0
	global_load_dwordx4 v[28:31], v[28:29], off offset:1280
	s_nop 0
	global_load_dwordx4 v[40:43], v[44:45], off offset:1344
	s_nop 0
	global_load_dwordx4 v[44:47], v[44:45], off offset:1280
	s_nop 0
	global_load_dwordx4 v[48:51], v[52:53], off offset:1344
	s_nop 0
	global_load_dwordx4 v[52:55], v[52:53], off offset:1280
	v_max_i32_e32 v76, -16, v86
	global_load_dwordx4 v[64:67], v[64:65], off offset:2048
	v_add_u32_e32 v76, 16, v76
	global_load_dwordx4 v[72:75], v[68:69], off offset:2048
	v_max_i32_e32 v68, 0xffffffe8, v86
	v_add_u32_e32 v68, 24, v68
	v_mad_u64_u32 v[68:69], s[20:21], v68, s5, v[84:85]
	v_mad_u64_u32 v[76:77], s[20:21], v76, s5, v[84:85]
	v_lshl_add_u64 v[68:69], v[68:69], 0, v[88:89]
	v_lshl_add_u64 v[76:77], v[76:77], 0, v[88:89]
	v_max_i32_e32 v56, 0xffffffc8, v86
	v_max_i32_e32 v60, 0xffffffd0, v86
	global_load_dwordx4 v[68:71], v[68:69], off offset:2048
	v_add_u32_e32 v56, 56, v56
	global_load_dwordx4 v[80:83], v[76:77], off offset:2048
	v_or_b32_e32 v76, 8, v86
	v_add_u32_e32 v60, 48, v60
	v_max_i32_e32 v76, 0, v76
	v_max_i32_e32 v86, 0, v86
	v_mad_u64_u32 v[56:57], s[20:21], v56, s5, v[84:85]
	v_mad_u64_u32 v[60:61], s[20:21], v60, s5, v[84:85]
	v_mad_u64_u32 v[76:77], s[20:21], v76, s5, v[84:85]
	v_mad_u64_u32 v[84:85], s[20:21], v86, s5, v[84:85]
	v_lshl_add_u64 v[56:57], v[56:57], 0, v[88:89]
	v_lshl_add_u64 v[60:61], v[60:61], 0, v[88:89]
	v_lshl_add_u64 v[76:77], v[76:77], 0, v[88:89]
	v_lshl_add_u64 v[84:85], v[84:85], 0, v[88:89]
	global_load_dwordx4 v[56:59], v[56:57], off offset:2048
	v_lshl_add_u64 v[128:129], s[0:1], 0, v[88:89]
	global_load_dwordx4 v[60:63], v[60:61], off offset:2048
	v_lshl_add_u64 v[130:131], s[0:1], 0, v[32:33]
	global_load_dwordx4 v[76:79], v[76:77], off offset:2048
	v_mov_b32_e32 v88, 0
	global_load_dwordx4 v[84:87], v[84:85], off offset:2048
	v_mov_b32_e32 v89, v153
	s_branch .LBB0_236

; #define LAS __attribute__((address_space(3)))
; __device__ __forceinline__ float bflo(unsigned u) { return __uint_as_float(u << 16); }
; __device__ __forceinline__ float bfhi(unsigned u) { return __uint_as_float(u & 0xffff0000u); }
; __device__ __forceinline__ float sx(float v, int m, int lane) { return __builtin_bit_cast(float, __builtin_amdgcn_ds_bpermute((lane ^ m) << 2, __builtin_bit_cast(int, v))); }
; __device__ __forceinline__ void sb_item(const bf16_t* hbuf, const float* kmax2, bf16_t* mixed, LAS bf16_t* vT, int item, int lane) {
;     const int bh = item >> 10, qt = item & 1023, b = bh / 6, h = bh % 6, tq0 = qt * 16; const size_t row0 = (size_t)b * SEQ + tq0;
;     const int r = lane & 15, q = lane >> 4;
;     bf16x8 qf[2]; float bound, carry = 0.f;
;     const float km2 = kmax2[bh];
;     { float s = 0.f;
; #pragma unroll
;       for (int ks = 0; ks < 2; ++ks) { const u32x4 v = *(const u32x4*)(hbuf + (row0 + r) * INWP + C_SBQ + h * 64 + 32 * ks + 8 * q); qf[ks] = as_bf16x8(v);
;           s += bflo(v.x) * bflo(v.x) + bfhi(v.x) * bfhi(v.x) + bflo(v.y) * bflo(v.y) + bfhi(v.y) * bfhi(v.y) + bflo(v.z) * bflo(v.z) + bfhi(v.z) * bfhi(v.z) + bflo(v.w) * bflo(v.w) + bfhi(v.w) * bfhi(v.w); }
;       s += sx(s, 16, lane); s += sx(s, 32, lane);
;       bound = sqrtf(s * km2) * 0.125f * 1.01f + 0.05f; }
;     const int qpos = tq0 + r;
;     f32x4 O[4];
; #pragma unroll
;     for (int et = 0; et < 4; ++et) O[et] = (f32x4){0.f, 0.f, 0.f, 0.f};
;     const int cr = lane >> 3, dc = lane & 7;
;     const bf16_t* seqp = hbuf + (size_t)b * SEQ * INWP + h * 64;
;     u32x4 vreg[8], kreg[8];
;     { const int k0 = tq0 + 16 - 64;
; #pragma unroll
;       for (int i = 0; i < 8; ++i) vreg[i] = *(const u32x4*)(seqp + (size_t)max(k0 + cr + 8 * i, 0) * INWP + C_SBV + 8 * dc);
; #pragma unroll
;       for (int i = 0; i < 8; ++i) kreg[i] = *(const u32x4*)(seqp + (size_t)max(k0 + 16 * (i >> 1) + r, 0) * INWP + C_SBK + 32 * (i & 1) + 8 * q); }
.LBB0_283:
	s_ashr_i32 s20, s15, 10
	s_mul_hi_i32 s0, s20, 0x2aaaaaab
	s_lshr_b32 s1, s0, 31
	s_add_i32 s0, s0, s1
	s_mul_i32 s1, s0, 6
	s_sub_i32 s17, s20, s1
	s_lshl_b32 s1, s15, 4
	s_and_b32 s26, s1, 0x3ff0
	s_ashr_i32 s1, s0, 31
	s_lshl_b64 s[22:23], s[0:1], 14
	s_ashr_i32 s21, s20, 31
	s_or_b32 s22, s22, s26
	s_lshl_b64 s[20:21], s[20:21], 2
	s_add_u32 s38, s75, s20
	v_lshl_add_u64 v[124:125], s[22:23], 0, v[122:123]
	v_mov_b64_e32 v[4:5], s[42:43]
	s_addc_u32 s39, s74, s21
	v_mad_u64_u32 v[4:5], s[20:21], v124, s5, v[4:5]
	v_mov_b32_e32 v6, v5
	v_mad_u64_u32 v[6:7], s[20:21], v125, s5, v[6:7]
	s_lshl_b32 s20, s17, 6
	s_ashr_i32 s21, s20, 31
	v_mov_b32_e32 v5, v6
	s_lshl_b64 s[22:23], s[20:21], 1
	v_lshl_add_u64 v[4:5], v[4:5], 0, s[22:23]
	s_waitcnt vmcnt(0)
	v_lshl_add_u64 v[8:9], v[4:5], 0, v[116:117]
	global_load_dwordx4 v[4:7], v[8:9], off offset:512
	global_load_dword v54, v33, s[38:39] offset:1024
	s_mul_hi_i32 s1, s0, 0x6000000
	global_load_dwordx4 v[8:11], v[8:9], off offset:576
	s_mul_i32 s0, s0, 0x6000000
	s_add_u32 s0, s42, s0
	s_addc_u32 s1, s43, s1
	s_add_u32 s22, s0, s22
	s_addc_u32 s23, s1, s23
	s_sub_i32 s17, s26, 48
	v_or_b32_e32 v12, s17, v130
	v_or_b32_e32 v55, s17, v134
	v_mov_b64_e32 v[48:49], s[22:23]
	v_max_i32_e32 v13, 0xffffffd0, v12
	v_max_i32_e32 v14, 0xffffffe0, v12
	v_max_i32_e32 v15, -16, v12
	v_max_i32_e32 v12, 0, v12
	v_max_i32_e32 v16, 0xffffffc8, v55
	v_max_i32_e32 v17, 0xffffffd0, v55
	v_max_i32_e32 v18, 0xffffffd8, v55
	v_max_i32_e32 v19, 0xffffffe0, v55
	v_add_u32_e32 v20, 48, v13
	v_add_u32_e32 v21, 32, v14
	v_add_u32_e32 v22, 16, v15
	v_mad_u64_u32 v[12:13], s[0:1], v12, s5, v[48:49]
	v_add_u32_e32 v23, 56, v16
	v_add_u32_e32 v24, 48, v17
	v_add_u32_e32 v26, 40, v18
	v_add_u32_e32 v28, 32, v19
	v_mad_u64_u32 v[14:15], s[0:1], v20, s5, v[48:49]
	v_mad_u64_u32 v[16:17], s[0:1], v21, s5, v[48:49]
	v_mad_u64_u32 v[18:19], s[0:1], v22, s5, v[48:49]
	v_lshl_add_u64 v[20:21], v[12:13], 0, v[116:117]
	v_mad_u64_u32 v[22:23], s[0:1], v23, s5, v[48:49]
	v_mad_u64_u32 v[24:25], s[0:1], v24, s5, v[48:49]
	v_mad_u64_u32 v[26:27], s[0:1], v26, s5, v[48:49]
	v_mad_u64_u32 v[28:29], s[0:1], v28, s5, v[48:49]
	v_lshl_add_u64 v[30:31], v[14:15], 0, v[116:117]
	v_lshl_add_u64 v[40:41], v[16:17], 0, v[116:117]
	v_lshl_add_u64 v[42:43], v[18:19], 0, v[116:117]
	global_load_dwordx4 v[12:15], v[20:21], off offset:1344
	global_load_dwordx4 v[16:19], v[20:21], off offset:1280
	v_lshl_add_u64 v[20:21], v[22:23], 0, v[118:119]
	v_lshl_add_u64 v[22:23], v[24:25], 0, v[118:119]
	v_lshl_add_u64 v[44:45], v[26:27], 0, v[118:119]
	v_lshl_add_u64 v[50:51], v[28:29], 0, v[118:119]
	global_load_dwordx4 v[68:71], v[30:31], off offset:1344
	global_load_dwordx4 v[72:75], v[30:31], off offset:1280
	global_load_dwordx4 v[56:59], v[40:41], off offset:1344
	global_load_dwordx4 v[60:63], v[40:41], off offset:1280
	s_nop 0
	global_load_dwordx4 v[28:31], v[42:43], off offset:1344
	s_nop 0
	global_load_dwordx4 v[40:43], v[42:43], off offset:1280
	s_nop 0
	global_load_dwordx4 v[24:27], v[20:21], off offset:2048
	s_nop 0
	global_load_dwordx4 v[20:23], v[22:23], off offset:2048
	v_mov_b32_e32 v142, 0
	v_or_b32_e32 v144, s26, v130
	v_lshl_add_u64 v[126:127], s[22:23], 0, v[118:119]
	v_lshl_add_u64 v[128:129], s[22:23], 0, v[116:117]
	v_mov_b32_e32 v76, 0
	v_mov_b32_e32 v77, v142
	v_mov_b32_e32 v78, v142
	v_mov_b32_e32 v79, v142
	v_mov_b32_e32 v65, v142
	v_mov_b32_e32 v66, v142
	v_mov_b32_e32 v67, v142
	s_waitcnt vmcnt(10)
	v_and_b32_e32 v47, 0xffff0000, v4
	v_lshlrev_b32_e32 v46, 16, v4
	v_mul_f32_e32 v64, v47, v47
	v_lshlrev_b32_e32 v52, 16, v5
	v_fmac_f32_e32 v64, v46, v46
	global_load_dwordx4 v[44:47], v[44:45], off offset:2048
	s_nop 0
	global_load_dwordx4 v[80:83], v[50:51], off offset:2048
	v_max_i32_e32 v50, 0xffffffe8, v55
	v_fmac_f32_e32 v64, v52, v52
	v_add_u32_e32 v50, 24, v50
	v_max_i32_e32 v52, -16, v55
	v_and_b32_e32 v53, 0xffff0000, v5
	v_mad_u64_u32 v[50:51], s[0:1], v50, s5, v[48:49]
	v_add_u32_e32 v52, 16, v52
	v_fmac_f32_e32 v64, v53, v53
	v_lshl_add_u64 v[50:51], v[50:51], 0, v[118:119]
	v_mad_u64_u32 v[52:53], s[0:1], v52, s5, v[48:49]
	v_lshl_add_u64 v[52:53], v[52:53], 0, v[118:119]
	global_load_dwordx4 v[88:91], v[50:51], off offset:2048
	global_load_dwordx4 v[84:87], v[52:53], off offset:2048
	v_or_b32_e32 v50, 8, v55
	v_max_i32_e32 v50, 0, v50
	v_mad_u64_u32 v[50:51], s[0:1], v50, s5, v[48:49]
	v_max_i32_e32 v52, 0, v55
	v_lshl_add_u64 v[50:51], v[50:51], 0, v[118:119]
	v_mad_u64_u32 v[48:49], s[0:1], v52, s5, v[48:49]
	v_lshl_add_u64 v[48:49], v[48:49], 0, v[118:119]
	global_load_dwordx4 v[92:95], v[50:51], off offset:2048
	global_load_dwordx4 v[96:99], v[48:49], off offset:2048
	v_lshlrev_b32_e32 v48, 16, v6
	v_fmac_f32_e32 v64, v48, v48
	v_and_b32_e32 v48, 0xffff0000, v6
	v_fmac_f32_e32 v64, v48, v48
	v_lshlrev_b32_e32 v48, 16, v7
	v_fmac_f32_e32 v64, v48, v48
	v_and_b32_e32 v48, 0xffff0000, v7
	v_and_b32_e32 v49, 0xffff0000, v8
	v_fmac_f32_e32 v64, v48, v48
	v_lshlrev_b32_e32 v48, 16, v8
	v_mul_f32_e32 v49, v49, v49
	v_fmac_f32_e32 v49, v48, v48
	v_lshlrev_b32_e32 v48, 16, v9
	v_fmac_f32_e32 v49, v48, v48
	v_and_b32_e32 v48, 0xffff0000, v9
	v_fmac_f32_e32 v49, v48, v48
	v_lshlrev_b32_e32 v48, 16, v10
	v_fmac_f32_e32 v49, v48, v48
	v_and_b32_e32 v48, 0xffff0000, v10
	v_fmac_f32_e32 v49, v48, v48
	v_lshlrev_b32_e32 v48, 16, v11
	v_fmac_f32_e32 v49, v48, v48
	v_and_b32_e32 v48, 0xffff0000, v11
	v_fmac_f32_e32 v49, v48, v48
	v_add_f32_e32 v48, v64, v49
	ds_bpermute_b32 v49, v132, v48
	s_mov_b32 s0, 0xf800000
	v_mov_b32_e32 v64, 0
	v_mov_b32_e32 v52, 0
	v_mov_b32_e32 v53, v142
	s_waitcnt lgkmcnt(0)
	v_add_f32_e32 v48, v48, v49
	ds_bpermute_b32 v49, v133, v48
	v_mov_b32_e32 v55, v142
	s_waitcnt lgkmcnt(0)
	v_add_f32_e32 v48, v48, v49
	v_mul_f32_e32 v48, v54, v48
	v_mul_f32_e32 v49, 0x4f800000, v48
	v_cmp_gt_f32_e32 vcc, s0, v48
	v_mov_b32_e32 v54, v142
	s_nop 0
	v_cndmask_b32_e32 v48, v48, v49, vcc
	v_sqrt_f32_e32 v49, v48
	s_nop 0
	v_add_u32_e32 v50, -1, v49
	v_fma_f32 v51, -v50, v49, v48
	v_cmp_ge_f32_e64 s[0:1], 0, v51
	v_add_u32_e32 v51, 1, v49
	s_nop 0
	v_cndmask_b32_e64 v50, v49, v50, s[0:1]
	v_fma_f32 v49, -v51, v49, v48
	v_cmp_lt_f32_e64 s[0:1], 0, v49
	s_nop 1
	v_cndmask_b32_e64 v49, v50, v51, s[0:1]
	v_mul_f32_e32 v50, 0x37800000, v49
	v_cndmask_b32_e32 v49, v49, v50, vcc
	v_cmp_class_f32_e32 vcc, v48, v209
	v_mov_b32_e32 v50, v142
	v_mov_b32_e32 v51, v142
	v_cndmask_b32_e32 v48, v49, v48, vcc
	v_mul_f32_e32 v48, 0x3e000000, v48
	v_fmamk_f32 v143, v48, 0x3f8147ae, v170
	v_mov_b32_e32 v48, 0
	v_mov_b32_e32 v49, v142
	s_branch .LBB0_285
